# K and V tiles staged by direct global-to-LDS loads (rotation/XOR swizzled unpadded LDS layout), no register staging in the attention loop
# speedup vs baseline: 1.0308x; 1.0088x over previous
; __device__ void item_attn(PP p, int qb, int b, int hh, u16* lds) {
;     ...
;   const int ntiles = 2 * qb + 2;
;   const int my_ntiles = 2 * qb + 1 + (w >> 1);
;   const u16* kg = p->K + (size_t)(b * 6 + hh) * SEQ * 96 + tid * 8;
;   const u16* vg = p->VT + (size_t)(b * 6 + hh) * SEQ * 64 + tid * 8;
;   const int id1 = tid + 256, id2 = tid + 512;
;   const int kl0 = (tid / 12) * KLD + (tid % 12) * 8;
;   const int kl1 = (id1 / 12) * KLD + (id1 % 12) * 8;
;   const int kl2 = (id2 / 12) * KLD + (id2 % 12) * 8;
;   const int vl = 64 * KLD + (tid >> 3) * VLD + (tid & 7) * 8;
;   AStage A, B;
;   as_load(B, kg, vg, 0);
;   as_load(A, kg, vg, 1);
;   as_store(B, lds, kl0, kl1, kl2, vl);
;   __syncthreads();
.LBB0_433:
	s_mul_hi_u32 s38, s40, 0xaaaaaaab
	s_lshr_b32 s82, s38, 2
	s_mul_i32 s38, s82, 6
	s_sub_i32 s57, s40, s38
	s_mov_b64 s[38:39], s[34:35]
	s_load_dwordx4 s[48:51], s[38:39], 0x120
	s_load_dwordx2 s[46:47], s[38:39], 0x130
	v_mov_b32_e32 v140, v174
	s_waitcnt vmcnt(1)
	v_sub_co_u32_e64 v8, s[0:1], 63, s45
	v_ashrrev_i32_e32 v0, 1, v140
	v_and_b32_e32 v0, 0xffffffe0, v0
	s_lshl_b64 s[58:59], s[82:83], 13
	s_mul_i32 s42, s40, 0x180000
	s_waitcnt vmcnt(0)
	v_lshl_add_u32 v2, v8, 7, v0
	s_mov_b32 s41, s83
	s_mul_hi_u32 s43, s40, 0x180000
	s_waitcnt lgkmcnt(0)
	s_add_u32 s42, s50, s42
	v_ashrrev_i32_e32 v3, 31, v2
	s_addc_u32 s43, s51, s43
	s_lshl_b64 s[40:41], s[40:41], 20
	v_and_b32_e32 v141, 31, v140
	v_lshl_add_u64 v[132:133], s[58:59], 0, v[2:3]
	s_add_u32 s46, s46, s40
	v_or_b32_e32 v131, v132, v141
	v_mov_b32_e32 v0, s57
	s_addc_u32 s47, s47, s41
	v_mov_b32_e32 v4, s48
	v_mov_b32_e32 v5, s49
	v_mad_u64_u32 v[2:3], s[40:41], v131, 6, v[0:1]
	v_mad_i32_i24 v6, v133, 6, v3
	v_mad_u64_u32 v[2:3], s[40:41], v2, s23, v[4:5]
	v_mov_b32_e32 v0, v3
	v_bfe_u32 v9, v140, 5, 1
	v_mad_u64_u32 v[4:5], s[40:41], v6, s23, v[0:1]
	v_mov_b32_e32 v3, v4
	v_lshlrev_b32_e32 v0, 4, v9
	v_lshl_add_u64 v[2:3], v[2:3], 0, v[0:1]
	global_load_dwordx4 v[66:69], v[2:3], off
	global_load_dwordx4 v[70:73], v[2:3], off offset:32
	global_load_dwordx4 v[74:77], v[2:3], off offset:64
	global_load_dwordx4 v[78:81], v[2:3], off offset:96
	global_load_dwordx4 v[82:85], v[2:3], off offset:128
	global_load_dwordx4 v[86:89], v[2:3], off offset:160
	v_lshlrev_b32_e32 v2, 3, v140
	v_ashrrev_i32_e32 v3, 31, v2
	v_lshlrev_b64 v[134:135], 1, v[2:3]
	v_lshl_add_u64 v[36:37], s[42:43], 0, v[134:135]
	v_add_co_u32_e32 v4, vcc, s4, v36
	v_lshl_add_u64 v[34:35], s[46:47], 0, v[134:135]
	s_nop 0
	v_addc_co_u32_e32 v5, vcc, 0, v37, vcc
	global_load_dwordx4 v[90:93], v[36:37], off
	global_load_dwordx4 v[94:97], v[4:5], off offset:-4096
	global_load_dwordx4 v[106:109], v[4:5], off
	global_load_dwordx4 v[114:117], v[34:35], off
	v_add_co_u32_e32 v4, vcc, s4, v34
	s_movk_i32 s40, 0x5000
	s_nop 0
	v_addc_co_u32_e32 v5, vcc, 0, v35, vcc
	v_add_co_u32_e32 v6, vcc, s2, v36
	v_mul_hi_i32 v0, v140, s95
	s_nop 0
	v_addc_co_u32_e32 v7, vcc, 0, v37, vcc
	global_load_dwordx4 v[98:101], v[6:7], off offset:-4096
	global_load_dwordx4 v[102:105], v[6:7], off
	v_add_co_u32_e32 v6, vcc, s40, v36
	s_movk_i32 s40, 0x3000
	s_nop 0
	v_addc_co_u32_e32 v7, vcc, 0, v37, vcc
	global_load_dwordx4 v[110:113], v[6:7], off
	global_load_dwordx4 v[122:125], v[4:5], off offset:-4096
	global_load_dwordx4 v[118:121], v[4:5], off
	v_add_co_u32_e32 v4, vcc, s40, v34
	v_add_u32_e32 v3, 0x100, v140
	s_nop 0
	v_addc_co_u32_e32 v5, vcc, 0, v35, vcc
	global_load_dwordx4 v[126:129], v[4:5], off
	v_lshrrev_b32_e32 v5, 31, v0
	v_lshrrev_b32_e32 v0, 1, v0
	v_add_u32_e32 v0, v0, v5
	v_mul_hi_i32 v5, v3, s95
	v_add_u32_e32 v4, 0x200, v140
	v_lshrrev_b32_e32 v6, 31, v5
	v_lshrrev_b32_e32 v5, 1, v5
	v_add_u32_e32 v5, v5, v6
	v_mul_hi_i32 v6, v4, s95
	v_lshrrev_b32_e32 v7, 31, v6
	v_lshrrev_b32_e32 v6, 1, v6
	v_add_u32_e32 v6, v6, v7
	v_lshrrev_b32_e32 v7, 3, v140
	v_mul_lo_u32 v7, v7, s85
	v_and_b32_e32 v2, 56, v2
	v_readfirstlane_b32 s44, v8
	v_lshlrev_b32_e32 v132, 3, v9
	v_mul_u32_u24_e32 v10, 12, v0
	v_sub_u32_e32 v10, v140, v10
	v_bfe_u32 v11, v0, 2, 2
	v_mul_u32_u24_e32 v12, 0xc0, v0
	v_sub_u32_e32 v13, v10, v11
	v_add_u32_e32 v13, 12, v13
	v_subrev_u32_e32 v14, 12, v13
	v_min_u32_e32 v13, v13, v14
	v_lshl_add_u32 v220, v13, 4, v12
	v_add_u32_e32 v13, v10, v11
	v_subrev_u32_e32 v14, 12, v13
	v_min_u32_e32 v13, v13, v14
	v_lshl_add_u32 v0, v13, 4, v12
	v_mul_u32_u24_e32 v10, 12, v5
	v_sub_u32_e32 v10, v3, v10
	v_bfe_u32 v11, v5, 2, 2
	v_mul_u32_u24_e32 v12, 0xc0, v5
	v_sub_u32_e32 v13, v10, v11
	v_add_u32_e32 v13, 12, v13
	v_subrev_u32_e32 v14, 12, v13
	v_min_u32_e32 v13, v13, v14
	v_lshl_add_u32 v221, v13, 4, v12
	v_add_u32_e32 v13, v10, v11
	v_subrev_u32_e32 v14, 12, v13
	v_min_u32_e32 v13, v13, v14
	v_lshl_add_u32 v154, v13, 4, v12
	v_mul_u32_u24_e32 v10, 12, v6
	v_sub_u32_e32 v10, v4, v10
	v_bfe_u32 v11, v6, 2, 2
	v_mul_u32_u24_e32 v12, 0xc0, v6
	v_sub_u32_e32 v13, v10, v11
	v_add_u32_e32 v13, 12, v13
	v_subrev_u32_e32 v14, 12, v13
	v_min_u32_e32 v13, v13, v14
	v_lshl_add_u32 v222, v13, 4, v12
	v_add_u32_e32 v13, v10, v11
	v_subrev_u32_e32 v14, 12, v13
	v_min_u32_e32 v13, v13, v14
	v_lshl_add_u32 v155, v13, 4, v12
	v_mul_u32_u24_e32 v10, 0xc0, v141
	v_bfe_u32 v11, v141, 2, 2
	v_add_u32_e32 v11, v11, v9
	v_add_u32_e32 v12, 0, v11
	v_subrev_u32_e32 v13, 12, v12
	v_min_u32_e32 v12, v12, v13
	v_lshl_add_u32 v214, v12, 4, v10
	v_add_u32_e32 v12, 2, v11
	v_subrev_u32_e32 v13, 12, v12
	v_min_u32_e32 v12, v12, v13
	v_lshl_add_u32 v215, v12, 4, v10
	v_add_u32_e32 v12, 4, v11
	v_subrev_u32_e32 v13, 12, v12
	v_min_u32_e32 v12, v12, v13
	v_lshl_add_u32 v216, v12, 4, v10
	v_add_u32_e32 v12, 6, v11
	v_subrev_u32_e32 v13, 12, v12
	v_min_u32_e32 v12, v12, v13
	v_lshl_add_u32 v217, v12, 4, v10
	v_add_u32_e32 v12, 8, v11
	v_subrev_u32_e32 v13, 12, v12
	v_min_u32_e32 v12, v12, v13
	v_lshl_add_u32 v218, v12, 4, v10
	v_add_u32_e32 v12, 10, v11
	v_subrev_u32_e32 v13, 12, v12
	v_min_u32_e32 v12, v12, v13
	v_lshl_add_u32 v219, v12, 4, v10
	v_add_lshl_u32 v156, v7, v2, 1
	v_lshrrev_b32_e32 v213, 4, v140
	v_and_b32_e32 v213, 7, v213
	v_and_b32_e32 v254, 7, v140
	v_xor_b32_e32 v213, v213, v254
	v_lshrrev_b32_e32 v254, 3, v140
	v_lshlrev_b32_e32 v254, 7, v254
	v_lshl_add_u32 v213, v213, 4, v254
	v_readfirstlane_b32 s62, v140
	s_nop 3
	s_lshl_b32 s62, s62, 4
	s_andn2_b64 vcc, exec, s[0:1]
	s_mov_b64 s[0:1], -1
	s_waitcnt vmcnt(9)
	ds_write_b128 v0, v[90:93]
	s_waitcnt vmcnt(8)
	ds_write_b128 v154, v[94:97]
	s_waitcnt vmcnt(7)
	ds_write_b128 v155, v[106:109]
	s_waitcnt vmcnt(6)
	ds_write_b128 v213, v[114:117] offset:13312
	s_waitcnt vmcnt(2)
	ds_write_b128 v213, v[122:125] offset:17408
	s_waitcnt lgkmcnt(0)
	s_barrier
	s_cbranch_vccz .LBB0_478
	s_cmp_lg_u32 s45, 63
	s_cselect_b64 s[0:1], -1, 0
	s_cmp_eq_u32 s45, 63
	s_cbranch_scc1 .LBB0_436
	v_add_co_u32_e32 v2, vcc, 0x6000, v36
	s_nop 1
	v_addc_co_u32_e32 v3, vcc, 0, v37, vcc
	v_add_co_u32_e32 v4, vcc, 0x7000, v36
	s_nop 1
	v_addc_co_u32_e32 v5, vcc, 0, v37, vcc
	global_load_dwordx4 v[90:93], v[2:3], off
	global_load_dwordx4 v[94:97], v[4:5], off
	v_add_co_u32_e32 v2, vcc, 0x8000, v36
	s_nop 1
	v_addc_co_u32_e32 v3, vcc, 0, v37, vcc
	global_load_dwordx4 v[106:109], v[2:3], off
	v_add_co_u32_e32 v2, vcc, 0x4000, v34
	s_nop 1
	v_addc_co_u32_e32 v3, vcc, 0, v35, vcc
	v_add_co_u32_e32 v4, vcc, 0x5000, v34
	s_nop 1
	v_addc_co_u32_e32 v5, vcc, 0, v35, vcc
	global_load_dwordx4 v[114:117], v[2:3], off
	global_load_dwordx4 v[122:125], v[4:5], off
; __device__ __forceinline__ void attn_tile(const u16* sb, const bf16x8 (&qa)[6], f32x16& o0, f32x16& o1, f32x16& lacc,
;                                           float& m, bool& mz, int r, int h, bool first) {
;   const u16* kp = sb + r * KLD + h * 8;
;   f32x16 s0, s1;
;   __builtin_amdgcn_s_setprio(1);
;   if (mz) {
; #pragma unroll
;     for (int i = 0; i < 16; ++i) { s0[i] = 0.f; s1[i] = 0.f; }
;     attn_qk(kp, qa, s0, s1);
;   } else {
; #pragma unroll
;     for (int i = 0; i < 16; ++i) { s0[i] = -m; s1[i] = -m; }
;     attn_qk(kp, qa, s0, s1);
;   }
;   __builtin_amdgcn_s_setprio(0);
;   float mxa = max3f(s0[0], s0[1], s0[2]), mxb = max3f(s0[3], s0[4], s0[5]);
;   float mxc = max3f(s0[6], s0[7], s0[8]), mxd = max3f(s0[9], s0[10], s0[11]);
;   mxa = max3f(mxa, s0[12], s0[13]); mxb = max3f(mxb, s0[14], s0[15]);
;   mxc = max3f(mxc, s1[0], s1[1]); mxd = max3f(mxd, s1[2], s1[3]);
;   mxa = max3f(mxa, s1[4], s1[5]); mxb = max3f(mxb, s1[6], s1[7]);
;   mxc = max3f(mxc, s1[8], s1[9]); mxd = max3f(mxd, s1[10], s1[11]);
;   mxa = max3f(mxa, s1[12], s1[13]); mxb = max3f(mxb, s1[14], s1[15]);
;   const float lm = max3f(mxa, mxb, fmaxf(mxc, mxd));
;   bool slow;
;   if (first) {
;     const float mx = fmaxf(lm, __shfl_xor(lm, 32));
;     slow = __any(mx > 30.f || mx < -30.f);
;   } else {
;     slow = __any(lm > 30.f);
;   }
;   if (slow) {
;     const float mx = fmaxf(lm, __shfl_xor(lm, 32));
;     const float d = first ? mx : fmaxf(mx, 0.f);
;     const float alpha = first ? 1.f : __builtin_amdgcn_exp2f(-d);
;     m += d;
;     mz = false;
; #pragma unroll
;     for (int i = 0; i < 16; ++i) { s0[i] -= d; s1[i] -= d; o0[i] *= alpha; o1[i] *= alpha; }
;     lacc[0] *= alpha;
;   }
.LBB0_436:
	v_mul_u32_u24_e32 v2, 0x68, v141
	v_lshlrev_b32_e32 v2, 1, v2
	v_lshl_add_u32 v157, v132, 1, v2
	s_setprio 1
	ds_read_b128 v[2:5], v214
	ds_read_b128 v[38:41], v215
	ds_read_b128 v[18:21], v214 offset:6144
	s_waitcnt lgkmcnt(2)
	v_mfma_f32_32x32x16_bf16 v[2:17], v[2:5], v[66:69], 0
	s_waitcnt lgkmcnt(1)
	v_mfma_f32_32x32x16_bf16 v[2:17], v[38:41], v[70:73], v[2:17]
	ds_read_b128 v[38:41], v215 offset:6144
	s_waitcnt lgkmcnt(1)
	v_mfma_f32_32x32x16_bf16 v[18:33], v[18:21], v[66:69], 0
	s_waitcnt lgkmcnt(0)
	v_mfma_f32_32x32x16_bf16 v[18:33], v[38:41], v[70:73], v[18:33]
	ds_read_b128 v[38:41], v216
	s_waitcnt lgkmcnt(0)
	v_mfma_f32_32x32x16_bf16 v[2:17], v[38:41], v[74:77], v[2:17]
	ds_read_b128 v[38:41], v216 offset:6144
	s_waitcnt lgkmcnt(0)
	v_mfma_f32_32x32x16_bf16 v[18:33], v[38:41], v[74:77], v[18:33]
	ds_read_b128 v[38:41], v217
	s_waitcnt lgkmcnt(0)
	v_mfma_f32_32x32x16_bf16 v[2:17], v[38:41], v[78:81], v[2:17]
	ds_read_b128 v[38:41], v217 offset:6144
	s_waitcnt lgkmcnt(0)
	v_mfma_f32_32x32x16_bf16 v[18:33], v[38:41], v[78:81], v[18:33]
	ds_read_b128 v[38:41], v218
	s_waitcnt lgkmcnt(0)
	v_mfma_f32_32x32x16_bf16 v[2:17], v[38:41], v[82:85], v[2:17]
	ds_read_b128 v[38:41], v218 offset:6144
	s_waitcnt lgkmcnt(0)
	v_mfma_f32_32x32x16_bf16 v[18:33], v[38:41], v[82:85], v[18:33]
	ds_read_b128 v[38:41], v219
	s_waitcnt lgkmcnt(0)
	v_mfma_f32_32x32x16_bf16 v[2:17], v[38:41], v[86:89], v[2:17]
	ds_read_b128 v[38:41], v219 offset:6144
	s_waitcnt lgkmcnt(0)
	v_mfma_f32_32x32x16_bf16 v[18:33], v[38:41], v[86:89], v[18:33]
	s_setprio 0
	v_max3_f32 v38, v2, v3, v4
	v_max3_f32 v39, v5, v6, v7
	v_max3_f32 v40, v8, v9, v10
	v_max3_f32 v41, v11, v12, v13
	v_mbcnt_hi_u32_b32 v160, -1, v183
	v_max3_f32 v38, v38, v14, v15
	v_max3_f32 v39, v39, v16, v17
	v_max3_f32 v40, v40, v18, v19
	v_max3_f32 v41, v41, v20, v21
	v_xor_b32_e32 v158, 32, v160
	v_max3_f32 v38, v38, v22, v23
	v_max3_f32 v39, v39, v24, v25
	v_max3_f32 v40, v40, v26, v27
	v_max3_f32 v41, v41, v28, v29
	s_nop 0
	v_max3_f32 v38, v38, v30, v31
	v_max3_f32 v39, v39, v32, v33
	v_max_f32_e32 v41, v41, v41
	v_max_f32_e32 v40, v40, v40
	v_max_f32_e32 v40, v40, v41
	v_max3_f32 v38, v38, v39, v40
	v_and_b32_e32 v39, 64, v160
	v_add_u32_e32 v159, 64, v39
	v_cmp_lt_i32_e32 vcc, v158, v159
	s_nop 1
	v_cndmask_b32_e32 v39, v160, v158, vcc
	v_lshlrev_b32_e32 v161, 2, v39
	ds_bpermute_b32 v40, v161, v38
	v_max_f32_e32 v39, v38, v38
	s_waitcnt lgkmcnt(0)
	v_max_f32_e32 v40, v40, v40
	v_max_f32_e32 v40, v39, v40
	v_cmp_gt_f32_e64 vcc, |v40|, s5
	s_cmp_eq_u64 vcc, 0
	s_cselect_b64 s[48:49], -1, 0
	s_cmp_lg_u64 vcc, 0
	s_cselect_b64 s[50:51], -1, 0
	s_cbranch_vccz .LBB0_439
	ds_bpermute_b32 v38, v161, v38
	s_waitcnt lgkmcnt(0)
	v_max_f32_e32 v38, v38, v38
	v_max_f32_e32 v38, v39, v38
	v_add_f32_e32 v162, 0, v38
	v_pk_add_f32 v[2:3], v[2:3], v[38:39] op_sel_hi:[1,0] neg_lo:[0,1] neg_hi:[0,1]
	v_pk_add_f32 v[18:19], v[18:19], v[38:39] op_sel_hi:[1,0] neg_lo:[0,1] neg_hi:[0,1]
	v_pk_add_f32 v[4:5], v[4:5], v[38:39] op_sel_hi:[1,0] neg_lo:[0,1] neg_hi:[0,1]
	v_pk_add_f32 v[20:21], v[20:21], v[38:39] op_sel_hi:[1,0] neg_lo:[0,1] neg_hi:[0,1]
	v_pk_add_f32 v[6:7], v[6:7], v[38:39] op_sel_hi:[1,0] neg_lo:[0,1] neg_hi:[0,1]
	v_pk_add_f32 v[22:23], v[22:23], v[38:39] op_sel_hi:[1,0] neg_lo:[0,1] neg_hi:[0,1]
	v_pk_add_f32 v[8:9], v[8:9], v[38:39] op_sel_hi:[1,0] neg_lo:[0,1] neg_hi:[0,1]
	v_pk_add_f32 v[24:25], v[24:25], v[38:39] op_sel_hi:[1,0] neg_lo:[0,1] neg_hi:[0,1]
	v_pk_add_f32 v[10:11], v[10:11], v[38:39] op_sel_hi:[1,0] neg_lo:[0,1] neg_hi:[0,1]
	v_pk_add_f32 v[26:27], v[26:27], v[38:39] op_sel_hi:[1,0] neg_lo:[0,1] neg_hi:[0,1]
	v_pk_add_f32 v[12:13], v[12:13], v[38:39] op_sel_hi:[1,0] neg_lo:[0,1] neg_hi:[0,1]
	v_pk_add_f32 v[28:29], v[28:29], v[38:39] op_sel_hi:[1,0] neg_lo:[0,1] neg_hi:[0,1]
	v_pk_add_f32 v[14:15], v[14:15], v[38:39] op_sel_hi:[1,0] neg_lo:[0,1] neg_hi:[0,1]
	v_pk_add_f32 v[30:31], v[30:31], v[38:39] op_sel_hi:[1,0] neg_lo:[0,1] neg_hi:[0,1]
	v_pk_add_f32 v[16:17], v[16:17], v[38:39] op_sel_hi:[1,0] neg_lo:[0,1] neg_hi:[0,1]
	v_pk_add_f32 v[32:33], v[32:33], v[38:39] op_sel_hi:[1,0] neg_lo:[0,1] neg_hi:[0,1]
	s_branch .LBB0_440

; __device__ __forceinline__ void attn_qk(const u16* kp, const bf16x8 (&qa)[6], f32x16& s0, f32x16& s1) {
; #pragma unroll
;   for (int ks = 0; ks < 6; ++ks) {
;     bf16x8 k0 = *(const bf16x8*)(kp + ks * 16);
;     bf16x8 k1 = *(const bf16x8*)(kp + 32 * KLD + ks * 16);
;     s0 = mfma32(k0, qa[ks], s0);
;     s1 = mfma32(k1, qa[ks], s1);
;   }
; }
; __device__ __forceinline__ void attn_tile(const u16* sb, const bf16x8 (&qa)[6], f32x16& o0, f32x16& o1, f32x16& lacc,
;                                           float& m, bool& mz, int r, int h, bool first) {
;   const u16* kp = sb + r * KLD + h * 8;
;   f32x16 s0, s1;
;   __builtin_amdgcn_s_setprio(1);
;   if (mz) {
; #pragma unroll
;     for (int i = 0; i < 16; ++i) { s0[i] = 0.f; s1[i] = 0.f; }
;     attn_qk(kp, qa, s0, s1);
;   } else {
; #pragma unroll
;     for (int i = 0; i < 16; ++i) { s0[i] = -m; s1[i] = -m; }
;     attn_qk(kp, qa, s0, s1);
;   }
.LBB0_442:
	v_pk_add_f32 v[34:35], v[138:139], v[60:61]
	v_pk_add_f32 v[36:37], v[136:137], v[58:59]
	v_pk_add_f32 v[34:35], v[34:35], 0 op_sel_hi:[1,0]
	v_pk_add_f32 v[46:47], v[48:49], v[46:47]
	v_pk_add_f32 v[34:35], v[36:37], v[34:35]
	v_pk_add_f32 v[36:37], v[64:65], v[56:57]
	v_pk_add_f32 v[42:43], v[44:45], v[42:43]
	v_pk_add_f32 v[34:35], v[36:37], v[34:35]
	v_pk_add_f32 v[36:37], v[62:63], v[54:55]
	v_pk_add_f32 v[38:39], v[40:41], v[38:39]
	v_pk_add_f32 v[34:35], v[36:37], v[34:35]
	v_pk_add_f32 v[36:37], v[52:53], v[50:51]
	s_lshl_b32 s44, s44, 1
	v_pk_add_f32 v[36:37], v[36:37], 0 op_sel_hi:[1,0]
	v_pk_add_f32 v[36:37], v[46:47], v[36:37]
	s_nop 0
	v_pk_add_f32 v[36:37], v[42:43], v[36:37]
	s_nop 0
	v_pk_add_f32 v[36:37], v[38:39], v[36:37]
	s_nop 0
	v_pk_add_f32 v[34:35], v[34:35], v[36:37]
	s_nop 0
	v_pk_add_f32 v[136:137], v[34:35], v[34:35] op_sel:[0,1] op_sel_hi:[1,0]
	v_ashrrev_i32_e32 v34, 7, v140
	v_add3_u32 v165, v34, s44, 1
	v_mov_b32_e32 v137, v157
	v_cmp_lt_i32_e32 vcc, 1, v165
	s_and_saveexec_b64 s[0:1], vcc
	s_cbranch_execz .LBB0_451
	s_setprio 1
	s_andn2_b64 vcc, exec, s[50:51]
	s_mov_b64 s[50:51], -1
	s_cbranch_vccnz .LBB0_445
	ds_read_b128 v[138:141], v214 offset:22528
	v_xor_b32_e32 v34, 0x80000000, v162
	v_mov_b32_e32 v35, v34
	v_mov_b32_e32 v36, v34
	v_mov_b32_e32 v37, v34
	v_mov_b32_e32 v38, v34
	v_mov_b32_e32 v39, v34
	v_mov_b32_e32 v40, v34
	v_mov_b32_e32 v41, v34
	v_mov_b32_e32 v42, v34
	v_mov_b32_e32 v43, v34
	v_mov_b32_e32 v44, v34
	v_mov_b32_e32 v45, v34
	v_mov_b32_e32 v46, v34
	v_mov_b32_e32 v47, v34
	v_mov_b32_e32 v48, v34
	v_mov_b32_e32 v49, v34
	s_mov_b64 s[50:51], 0
	s_waitcnt lgkmcnt(0)
	v_mfma_f32_32x32x16_bf16 v[50:65], v[138:141], v[66:69], v[34:49]
	ds_read_b128 v[138:141], v214 offset:28672
	s_waitcnt lgkmcnt(0)
	v_mfma_f32_32x32x16_bf16 v[34:49], v[138:141], v[66:69], v[34:49]
	ds_read_b128 v[138:141], v215 offset:22528
	s_waitcnt lgkmcnt(0)
	v_mfma_f32_32x32x16_bf16 v[50:65], v[138:141], v[70:73], v[50:65]
	ds_read_b128 v[138:141], v215 offset:28672
	s_waitcnt lgkmcnt(0)
	v_mfma_f32_32x32x16_bf16 v[34:49], v[138:141], v[70:73], v[34:49]
	ds_read_b128 v[138:141], v216 offset:22528
	s_waitcnt lgkmcnt(0)
	v_mfma_f32_32x32x16_bf16 v[50:65], v[138:141], v[74:77], v[50:65]
	ds_read_b128 v[138:141], v216 offset:28672
	s_waitcnt lgkmcnt(0)
	v_mfma_f32_32x32x16_bf16 v[34:49], v[138:141], v[74:77], v[34:49]
	ds_read_b128 v[138:141], v217 offset:22528
	s_waitcnt lgkmcnt(0)
	v_mfma_f32_32x32x16_bf16 v[50:65], v[138:141], v[78:81], v[50:65]
	ds_read_b128 v[138:141], v217 offset:28672
	s_waitcnt lgkmcnt(0)
	v_mfma_f32_32x32x16_bf16 v[34:49], v[138:141], v[78:81], v[34:49]
	ds_read_b128 v[138:141], v218 offset:22528
	s_waitcnt lgkmcnt(0)
	v_mfma_f32_32x32x16_bf16 v[50:65], v[138:141], v[82:85], v[50:65]
	ds_read_b128 v[138:141], v218 offset:28672
	s_waitcnt lgkmcnt(0)
	v_mfma_f32_32x32x16_bf16 v[34:49], v[138:141], v[82:85], v[34:49]
	ds_read_b128 v[138:141], v219 offset:22528
	s_waitcnt lgkmcnt(0)
	v_mfma_f32_32x32x16_bf16 v[50:65], v[138:141], v[86:89], v[50:65]
	ds_read_b128 v[138:141], v219 offset:28672
	s_waitcnt lgkmcnt(0)
	v_mfma_f32_32x32x16_bf16 v[34:49], v[138:141], v[86:89], v[34:49]
.LBB0_445:
	s_andn2_b64 vcc, exec, s[50:51]
	s_cbranch_vccnz .LBB0_447
	s_nop 9
	ds_read_b128 v[34:37], v214 offset:22528
	ds_read_b128 v[138:141], v215 offset:22528
	s_waitcnt lgkmcnt(1)
	v_mfma_f32_32x32x16_bf16 v[50:65], v[34:37], v[66:69], 0
	ds_read_b128 v[34:37], v214 offset:28672
	s_waitcnt lgkmcnt(1)
	v_mfma_f32_32x32x16_bf16 v[50:65], v[138:141], v[70:73], v[50:65]
	ds_read_b128 v[138:141], v215 offset:28672
	s_waitcnt lgkmcnt(1)
	v_mfma_f32_32x32x16_bf16 v[34:49], v[34:37], v[66:69], 0
	s_waitcnt lgkmcnt(0)
	v_mfma_f32_32x32x16_bf16 v[34:49], v[138:141], v[70:73], v[34:49]
	ds_read_b128 v[138:141], v216 offset:22528
	s_waitcnt lgkmcnt(0)
	v_mfma_f32_32x32x16_bf16 v[50:65], v[138:141], v[74:77], v[50:65]
	ds_read_b128 v[138:141], v216 offset:28672
	s_waitcnt lgkmcnt(0)
	v_mfma_f32_32x32x16_bf16 v[34:49], v[138:141], v[74:77], v[34:49]
	ds_read_b128 v[138:141], v217 offset:22528
	s_waitcnt lgkmcnt(0)
	v_mfma_f32_32x32x16_bf16 v[50:65], v[138:141], v[78:81], v[50:65]
	ds_read_b128 v[138:141], v217 offset:28672
	s_waitcnt lgkmcnt(0)
	v_mfma_f32_32x32x16_bf16 v[34:49], v[138:141], v[78:81], v[34:49]
	ds_read_b128 v[138:141], v218 offset:22528
	s_waitcnt lgkmcnt(0)
	v_mfma_f32_32x32x16_bf16 v[50:65], v[138:141], v[82:85], v[50:65]
	ds_read_b128 v[138:141], v218 offset:28672
	s_waitcnt lgkmcnt(0)
	v_mfma_f32_32x32x16_bf16 v[34:49], v[138:141], v[82:85], v[34:49]
	ds_read_b128 v[138:141], v219 offset:22528
	s_waitcnt lgkmcnt(0)
	v_mfma_f32_32x32x16_bf16 v[50:65], v[138:141], v[86:89], v[50:65]
	ds_read_b128 v[138:141], v219 offset:28672
	s_waitcnt lgkmcnt(0)
	v_mfma_f32_32x32x16_bf16 v[34:49], v[138:141], v[86:89], v[34:49]

; __device__ void item_attn(PP p, int qb, int b, int hh, u16* lds) {
;     ...
;   for (int kt = 0; kt < ntiles; kt += 2) {
;     if (kt + 2 < ntiles) as_load(B, kg, vg, kt + 2);
;     attn_tile(lds, qa, oa0, oa1, lacc, ma, mz, r, h, kt == 0);
;     as_store(A, lds + ATT_STAGE, kl0, kl1, kl2, vl);
;     __syncthreads();
;     if (kt + 3 < ntiles) as_load(A, kg, vg, kt + 3);
;     if (kt + 1 < my_ntiles) attn_tile(lds + ATT_STAGE, qa, oa0, oa1, lacc, ma, mz, r, h, false);
;     if (kt + 2 < ntiles) as_store(B, lds, kl0, kl1, kl2, vl);
;     __syncthreads();
;   }
.LBB0_453:
	s_and_b64 vcc, exec, s[40:41]
	s_waitcnt lgkmcnt(0)
	s_barrier
	s_cbranch_vccnz .LBB0_477
	v_mov_b32_e32 v90, v214
	v_mov_b32_e32 v91, v215
	v_mov_b32_e32 v92, v216
	v_mov_b32_e32 v93, v217
	v_mov_b32_e32 v94, v218
	v_mov_b32_e32 v95, v219
	v_mov_b32_e32 v96, v220
	v_mov_b32_e32 v97, v221
	v_mov_b32_e32 v106, v222
	s_mov_b32 s45, 3
	s_branch .LBB0_456

; __device__ __forceinline__ void attn_tile(const u16* sb, const bf16x8 (&qa)[6], f32x16& o0, f32x16& o1, f32x16& lacc,
;                                           float& m, bool& mz, int r, int h, bool first) {
;   const u16* kp = sb + r * KLD + h * 8;
;   f32x16 s0, s1;
;   __builtin_amdgcn_s_setprio(1);
;   if (mz) {
; #pragma unroll
;     for (int i = 0; i < 16; ++i) { s0[i] = 0.f; s1[i] = 0.f; }
;     attn_qk(kp, qa, s0, s1);
;   } else {
; #pragma unroll
;     for (int i = 0; i < 16; ++i) { s0[i] = -m; s1[i] = -m; }
;     attn_qk(kp, qa, s0, s1);
;   }
; __device__ void item_attn(PP p, int qb, int b, int hh, u16* lds) {
;     ...
;     if (kt + 2 < ntiles) as_load(B, kg, vg, kt + 2);
.LBB0_456:
	s_add_u32 s60, s42, 0x9000
	s_addc_u32 s61, s43, 0
	s_add_u32 m0, s62, 22528
	s_nop 0
	global_load_lds_dwordx4 v96, s[60:61]
	s_add_u32 m0, s62, 26624
	s_nop 0
	global_load_lds_dwordx4 v97, s[60:61]
	s_add_u32 m0, s62, 30720
	s_nop 0
	global_load_lds_dwordx4 v106, s[60:61]
	s_add_u32 s60, s46, 0x6000
	s_addc_u32 s61, s47, 0
	s_add_u32 m0, s62, 35840
	s_nop 0
	global_load_lds_dwordx4 v213, s[60:61]
	s_add_u32 s60, s60, 0x1000
	s_addc_u32 s61, s61, 0
	s_add_u32 m0, s62, 39936
	s_nop 0
	global_load_lds_dwordx4 v213, s[60:61]
	s_add_i32 s58, s45, -1
	s_cmp_lt_i32 s58, s44
	s_cselect_b64 s[0:1], -1, 0
	s_cmp_ge_i32 s58, s44
	s_cbranch_scc1 .LBB0_458
.LBB0_458:
	ds_read_b128 v[214:217], v90
	ds_read_b128 v[218:221], v90 offset:6144
	ds_read_b128 v[222:225], v91
	ds_read_b128 v[226:229], v91 offset:6144
	ds_read_b128 v[230:233], v92
	ds_read_b128 v[234:237], v92 offset:6144
	ds_read_b128 v[238:241], v93
	ds_read_b128 v[242:245], v93 offset:6144
	ds_read_b128 v[246:249], v94
	ds_read_b128 v[250:253], v94 offset:6144
	ds_read_b128 v[142:145], v95
	ds_read_b128 v[146:149], v95 offset:6144
	s_setprio 1
	s_cmp_lg_u64 s[48:49], 0
	s_cbranch_scc1 .Lmz_e
	v_xor_b32_e32 v34, 0x80000000, v162
	v_mov_b32_e32 v35, v34
	v_mov_b32_e32 v36, v34
	v_mov_b32_e32 v37, v34
	v_mov_b32_e32 v38, v34
	v_mov_b32_e32 v39, v34
	v_mov_b32_e32 v40, v34
	v_mov_b32_e32 v41, v34
	v_mov_b32_e32 v42, v34
	v_mov_b32_e32 v43, v34
	v_mov_b32_e32 v44, v34
	v_mov_b32_e32 v45, v34
	v_mov_b32_e32 v46, v34
	v_mov_b32_e32 v47, v34
	v_mov_b32_e32 v48, v34
	v_mov_b32_e32 v49, v34
	s_waitcnt lgkmcnt(8)
	s_nop 0
	v_mfma_f32_32x32x16_bf16 v[50:65], v[214:217], v[66:69], v[34:49]
	v_mfma_f32_32x32x16_bf16 v[34:49], v[218:221], v[66:69], v[34:49]
	v_mfma_f32_32x32x16_bf16 v[50:65], v[222:225], v[70:73], v[50:65]
	v_mfma_f32_32x32x16_bf16 v[34:49], v[226:229], v[70:73], v[34:49]
	s_waitcnt lgkmcnt(4)
	v_mfma_f32_32x32x16_bf16 v[50:65], v[230:233], v[74:77], v[50:65]
	v_mfma_f32_32x32x16_bf16 v[34:49], v[234:237], v[74:77], v[34:49]
	v_mfma_f32_32x32x16_bf16 v[50:65], v[238:241], v[78:81], v[50:65]
	v_mfma_f32_32x32x16_bf16 v[34:49], v[242:245], v[78:81], v[34:49]
	s_waitcnt lgkmcnt(0)
	v_mfma_f32_32x32x16_bf16 v[50:65], v[246:249], v[82:85], v[50:65]
	v_mfma_f32_32x32x16_bf16 v[34:49], v[250:253], v[82:85], v[34:49]
	v_mfma_f32_32x32x16_bf16 v[50:65], v[142:145], v[86:89], v[50:65]
	v_mfma_f32_32x32x16_bf16 v[34:49], v[146:149], v[86:89], v[34:49]
	s_branch .Lqkd_e

; __device__ __forceinline__ void attn_tile(const u16* sb, const bf16x8 (&qa)[6], f32x16& o0, f32x16& o1, f32x16& lacc,
;                                           float& m, bool& mz, int r, int h, bool first) {
;     ...
;   float pa = 0.f, pb = 0.f, pc = 0.f, pd = 0.f;
; #pragma unroll
;   for (int i = 0; i < 16; ++i) {
;     s0[i] = __builtin_amdgcn_exp2f(s0[i]); s1[i] = __builtin_amdgcn_exp2f(s1[i]);
;     if ((i & 3) == 0) pa += s0[i] + s1[i];
;     else if ((i & 3) == 1) pb += s0[i] + s1[i];
;     else if ((i & 3) == 2) pc += s0[i] + s1[i];
;     else pd += s0[i] + s1[i];
;   }
;   lacc[0] += (pa + pb) + (pc + pd);
;   const u16* vp = sb + 64 * KLD + r * VLD + 8 * h;
;   __builtin_amdgcn_s_setprio(1);
; #pragma unroll
;   for (int kb = 0; kb < 2; ++kb) {
; #pragma unroll
;     for (int s = 0; s < 2; ++s) {
;       const bf16x8 pf = pack_p(kb == 0 ? s0 : s1, 8 * s);
;       const int koff = kb * 32 + 16 * s;
;       const bf16x8 v0 = *(const bf16x8*)(vp + koff);
;       const bf16x8 v1 = *(const bf16x8*)(vp + 32 * VLD + koff);
;       o0 = mfma32(v0, pf, o0);
;       o1 = mfma32(v1, pf, o1);
;     }
;   }
;   __builtin_amdgcn_s_setprio(0);
; __device__ void item_attn(PP p, int qb, int b, int hh, u16* lds) {
;     ...
;     as_store(A, lds + ATT_STAGE, kl0, kl1, kl2, vl);
;     __syncthreads();
;     if (kt + 3 < ntiles) as_load(A, kg, vg, kt + 3);
;     if (kt + 1 < my_ntiles) attn_tile(lds + ATT_STAGE, qa, oa0, oa1, lacc, ma, mz, r, h, false);
.LBB0_464:
	v_exp_f32_e32 v147, v53
	v_exp_f32_e32 v149, v37
	v_exp_f32_e32 v145, v57
	v_exp_f32_e32 v53, v41
	v_exp_f32_e32 v143, v61
	v_exp_f32_e32 v45, v45
	v_exp_f32_e32 v37, v65
	v_exp_f32_e32 v41, v49
	v_exp_f32_e32 v146, v34
	v_exp_f32_e32 v152, v35
	v_exp_f32_e32 v153, v36
	v_exp_f32_e32 v144, v38
	v_exp_f32_e32 v150, v39
	v_exp_f32_e32 v151, v40
	v_exp_f32_e32 v142, v42
	v_exp_f32_e32 v38, v43
	v_exp_f32_e32 v39, v44
	v_exp_f32_e32 v36, v46
	v_exp_f32_e32 v34, v47
	v_exp_f32_e32 v35, v48
	v_exp_f32_e32 v148, v50
	v_exp_f32_e32 v50, v51
	v_exp_f32_e32 v51, v52
	v_exp_f32_e32 v52, v54
	v_exp_f32_e32 v48, v55
	v_exp_f32_e32 v49, v56
	v_exp_f32_e32 v44, v58
	v_exp_f32_e32 v46, v59
	v_exp_f32_e32 v47, v60
	v_exp_f32_e32 v40, v62
	v_exp_f32_e32 v42, v63
	v_exp_f32_e32 v43, v64
	s_setprio 1
	v_cvt_pk_bf16_f32 v58, v148, v50
	v_cvt_pk_bf16_f32 v59, v51, v147
	v_cvt_pk_bf16_f32 v60, v52, v48
	v_cvt_pk_bf16_f32 v61, v49, v145
	v_cvt_pk_bf16_f32 v246, v44, v46
	v_cvt_pk_bf16_f32 v247, v47, v143
	v_cvt_pk_bf16_f32 v248, v40, v42
	v_cvt_pk_bf16_f32 v249, v43, v37
	s_waitcnt lgkmcnt(0)
	v_mfma_f32_32x32x16_bf16 v[18:33], v[214:217], v[58:61], v[18:33]
	v_mfma_f32_32x32x16_bf16 v[2:17], v[218:221], v[58:61], v[2:17]
	v_cvt_pk_bf16_f32 v58, v146, v152
	v_cvt_pk_bf16_f32 v59, v153, v149
	v_cvt_pk_bf16_f32 v60, v144, v150
	v_cvt_pk_bf16_f32 v61, v151, v53
	v_mfma_f32_32x32x16_bf16 v[18:33], v[222:225], v[246:249], v[18:33]
	v_mfma_f32_32x32x16_bf16 v[2:17], v[226:229], v[246:249], v[2:17]
	v_cvt_pk_bf16_f32 v246, v142, v38
	v_cvt_pk_bf16_f32 v247, v39, v45
	v_cvt_pk_bf16_f32 v248, v36, v34
	v_cvt_pk_bf16_f32 v249, v35, v41
	v_mfma_f32_32x32x16_bf16 v[18:33], v[230:233], v[58:61], v[18:33]
	v_mfma_f32_32x32x16_bf16 v[2:17], v[234:237], v[58:61], v[2:17]
	v_mfma_f32_32x32x16_bf16 v[18:33], v[238:241], v[246:249], v[18:33]
	v_mfma_f32_32x32x16_bf16 v[2:17], v[242:245], v[246:249], v[2:17]
	s_setprio 0
	s_waitcnt vmcnt(0)
	s_cmp_ge_i32 s45, s44
	s_waitcnt lgkmcnt(0)
	s_barrier
	s_cbranch_scc1 .LBB0_466
.LBB0_466:
	s_cmp_eq_u64 s[0:1], 0
	s_cbranch_scc1 .Lvd_skip
	s_add_u32 s60, s42, 0xc000
	s_addc_u32 s61, s43, 0
	s_add_u32 m0, s62, 0
	s_nop 0
	global_load_lds_dwordx4 v96, s[60:61]
	s_add_u32 m0, s62, 4096
	s_nop 0
	global_load_lds_dwordx4 v97, s[60:61]
	s_add_u32 m0, s62, 8192
	s_nop 0
	global_load_lds_dwordx4 v106, s[60:61]
	s_add_u32 s60, s46, 0x8000
	s_addc_u32 s61, s47, 0
	s_add_u32 m0, s62, 13312
	s_nop 0
	global_load_lds_dwordx4 v213, s[60:61]
	s_add_u32 s60, s60, 0x1000
	s_addc_u32 s61, s61, 0
	s_add_u32 m0, s62, 17408
	s_nop 0
	global_load_lds_dwordx4 v213, s[60:61]
.Lvd_skip:
	v_pk_add_f32 v[50:51], v[50:51], v[152:153]
	v_pk_add_f32 v[48:49], v[48:49], v[150:151]
	v_pk_add_f32 v[38:39], v[46:47], v[38:39]
	v_pk_add_f32 v[48:49], v[48:49], v[50:51]
	v_pk_add_f32 v[34:35], v[42:43], v[34:35]
	v_pk_add_f32 v[38:39], v[38:39], v[48:49]
	v_pk_add_f32 v[42:43], v[52:53], v[144:145]
	v_pk_add_f32 v[34:35], v[34:35], v[38:39]
	v_pk_add_f32 v[38:39], v[148:149], v[146:147]
	v_pk_add_f32 v[36:37], v[40:41], v[36:37]
	v_cmp_lt_i32_e32 vcc, s45, v165
	v_pk_add_f32 v[38:39], v[42:43], v[38:39]
	v_pk_add_f32 v[42:43], v[44:45], v[142:143]
	s_nop 0
	v_pk_add_f32 v[38:39], v[42:43], v[38:39]
	s_nop 0
	v_pk_add_f32 v[36:37], v[36:37], v[38:39]
	s_nop 0
	v_pk_add_f32 v[34:35], v[34:35], v[36:37]
	s_nop 0
	v_add_f32_e32 v34, v34, v35
	v_add_f32_e32 v136, v136, v34
	s_and_saveexec_b64 s[40:41], vcc
	s_cbranch_execz .LBB0_475
	ds_read_b128 v[214:217], v90 offset:22528
	ds_read_b128 v[218:221], v90 offset:28672
	ds_read_b128 v[222:225], v91 offset:22528
	ds_read_b128 v[226:229], v91 offset:28672
	ds_read_b128 v[230:233], v92 offset:22528
	ds_read_b128 v[234:237], v92 offset:28672
	ds_read_b128 v[238:241], v93 offset:22528
	ds_read_b128 v[242:245], v93 offset:28672
	ds_read_b128 v[246:249], v94 offset:22528
	ds_read_b128 v[250:253], v94 offset:28672
	ds_read_b128 v[142:145], v95 offset:22528
	ds_read_b128 v[146:149], v95 offset:28672
	s_setprio 1
	s_cmp_lg_u64 s[48:49], 0
	s_cbranch_scc1 .Lmz_o
	v_xor_b32_e32 v34, 0x80000000, v162
	v_mov_b32_e32 v35, v34
	v_mov_b32_e32 v36, v34
	v_mov_b32_e32 v37, v34
	v_mov_b32_e32 v38, v34
	v_mov_b32_e32 v39, v34
	v_mov_b32_e32 v40, v34
	v_mov_b32_e32 v41, v34
	v_mov_b32_e32 v42, v34
	v_mov_b32_e32 v43, v34
	v_mov_b32_e32 v44, v34
	v_mov_b32_e32 v45, v34
	v_mov_b32_e32 v46, v34
	v_mov_b32_e32 v47, v34
	v_mov_b32_e32 v48, v34
	v_mov_b32_e32 v49, v34
	s_waitcnt lgkmcnt(8)
	s_nop 0
	v_mfma_f32_32x32x16_bf16 v[50:65], v[214:217], v[66:69], v[34:49]
	v_mfma_f32_32x32x16_bf16 v[34:49], v[218:221], v[66:69], v[34:49]
	v_mfma_f32_32x32x16_bf16 v[50:65], v[222:225], v[70:73], v[50:65]
	v_mfma_f32_32x32x16_bf16 v[34:49], v[226:229], v[70:73], v[34:49]
	s_waitcnt lgkmcnt(4)
	v_mfma_f32_32x32x16_bf16 v[50:65], v[230:233], v[74:77], v[50:65]
	v_mfma_f32_32x32x16_bf16 v[34:49], v[234:237], v[74:77], v[34:49]
	v_mfma_f32_32x32x16_bf16 v[50:65], v[238:241], v[78:81], v[50:65]
	v_mfma_f32_32x32x16_bf16 v[34:49], v[242:245], v[78:81], v[34:49]
	s_waitcnt lgkmcnt(0)
	v_mfma_f32_32x32x16_bf16 v[50:65], v[246:249], v[82:85], v[50:65]
	v_mfma_f32_32x32x16_bf16 v[34:49], v[250:253], v[82:85], v[34:49]
	v_mfma_f32_32x32x16_bf16 v[50:65], v[142:145], v[86:89], v[50:65]
	v_mfma_f32_32x32x16_bf16 v[34:49], v[146:149], v[86:89], v[34:49]
	s_branch .Lqkd_o

; __device__ void item_attn(PP p, int qb, int b, int hh, u16* lds) {
;     ...
;     if (kt + 1 < my_ntiles) attn_tile(lds + ATT_STAGE, qa, oa0, oa1, lacc, ma, mz, r, h, false);
;     if (kt + 2 < ntiles) as_store(B, lds, kl0, kl1, kl2, vl);
;     __syncthreads();
;   }
.LBB0_475:
	s_or_b64 exec, exec, s[40:41]
	s_andn2_b64 vcc, exec, s[0:1]
	s_cbranch_vccnz .LBB0_455
	s_waitcnt vmcnt(0)
	s_branch .LBB0_455
